# NSA selected branch: hand-scheduled fast path for unmasked both-block chunks
# speedup vs baseline: 1.0115x; 1.0115x over previous
.LBB0_363:
	s_andn2_saveexec_b64 s[2:3], s[62:63]
	s_cbranch_execz .LBB0_369
	v_readfirstlane_b32 s1, v176
	s_add_i32 s0, s68, 0x7f
	s_nop 0
	s_cmp_le_i32 s0, s1
	s_cbranch_scc0 .Lnsa_both_slow
	v_add3_u32 v1, s90, v151, v152
	v_add3_u32 v179, s90, v154, v155
	ds_read_b128 v[180:183], v1
	ds_read_b128 v[184:187], v1 offset:4608
	ds_read_b128 v[188:191], v1 offset:32
	ds_read_b128 v[192:195], v1 offset:4640
	ds_read_b128 v[196:199], v1 offset:64
	ds_read_b128 v[200:203], v1 offset:4672
	ds_read_b128 v[204:207], v1 offset:96
	ds_read_b128 v[208:211], v1 offset:4704
	ds_read_b128 v[212:215], v1 offset:9216
	ds_read_b128 v[216:219], v1 offset:13824
	ds_read_b128 v[236:239], v1 offset:9248
	ds_read_b128 v[240:243], v1 offset:13856
	ds_read_b128 v[244:247], v1 offset:9280
	ds_read_b128 v[248:251], v1 offset:13888
	v_mov_b32_e32 v220, s87
	v_cndmask_b32_e64 v142, v234, -v220, vcc
	v_cndmask_b32_e64 v144, v234, -v220, s[50:51]
	v_mov_b32_e32 v168, 0x3e38aa3b
	s_waitcnt lgkmcnt(12)
	v_mfma_f32_32x32x16_bf16 v[34:49], v[180:183], v[98:101], 0
	v_mfma_f32_32x32x16_bf16 v[50:65], v[184:187], v[98:101], 0
	s_waitcnt lgkmcnt(10)
	v_mfma_f32_32x32x16_bf16 v[34:49], v[188:191], v[102:105], v[34:49]
	v_mfma_f32_32x32x16_bf16 v[50:65], v[192:195], v[102:105], v[50:65]
	ds_read_b128 v[180:183], v1 offset:9312
	ds_read_b128 v[184:187], v1 offset:13920
	s_waitcnt lgkmcnt(10)
	v_mfma_f32_32x32x16_bf16 v[34:49], v[196:199], v[106:109], v[34:49]
	v_mfma_f32_32x32x16_bf16 v[50:65], v[200:203], v[106:109], v[50:65]
	s_waitcnt lgkmcnt(8)
	v_mfma_f32_32x32x16_bf16 v[34:49], v[204:207], v[110:113], v[34:49]
	v_mfma_f32_32x32x16_bf16 v[50:65], v[208:211], v[110:113], v[50:65]
	s_waitcnt lgkmcnt(6)
	v_mfma_f32_32x32x16_bf16 v[66:81], v[212:215], v[98:101], 0
	v_mfma_f32_32x32x16_bf16 v[82:97], v[216:219], v[98:101], 0
	s_waitcnt lgkmcnt(4)
	v_mfma_f32_32x32x16_bf16 v[66:81], v[236:239], v[102:105], v[66:81]
	v_mfma_f32_32x32x16_bf16 v[82:97], v[240:243], v[102:105], v[82:97]
	s_waitcnt lgkmcnt(2)
	v_mfma_f32_32x32x16_bf16 v[66:81], v[244:247], v[106:109], v[66:81]
	v_mfma_f32_32x32x16_bf16 v[82:97], v[248:251], v[106:109], v[82:97]
	s_waitcnt lgkmcnt(0)
	v_mfma_f32_32x32x16_bf16 v[66:81], v[180:183], v[110:113], v[66:81]
	v_mfma_f32_32x32x16_bf16 v[82:97], v[184:187], v[110:113], v[82:97]
	s_nop 1
	v_mov_b64_e32 v[220:221], 0
	v_pk_fma_f32 v[34:35], v[34:35], v[168:169], v[142:143] op_sel_hi:[1,0,0]
	v_pk_fma_f32 v[36:37], v[36:37], v[168:169], v[142:143] op_sel_hi:[1,0,0]
	v_pk_fma_f32 v[38:39], v[38:39], v[168:169], v[142:143] op_sel_hi:[1,0,0]
	v_pk_fma_f32 v[40:41], v[40:41], v[168:169], v[142:143] op_sel_hi:[1,0,0]
	v_pk_fma_f32 v[42:43], v[42:43], v[168:169], v[142:143] op_sel_hi:[1,0,0]
	v_pk_fma_f32 v[44:45], v[44:45], v[168:169], v[142:143] op_sel_hi:[1,0,0]
	v_pk_fma_f32 v[46:47], v[46:47], v[168:169], v[142:143] op_sel_hi:[1,0,0]
	v_pk_fma_f32 v[48:49], v[48:49], v[168:169], v[142:143] op_sel_hi:[1,0,0]
	v_exp_f32_e32 v34, v34
	v_exp_f32_e32 v35, v35
	v_exp_f32_e32 v36, v36
	v_exp_f32_e32 v37, v37
	v_exp_f32_e32 v38, v38
	v_exp_f32_e32 v39, v39
	v_exp_f32_e32 v40, v40
	v_exp_f32_e32 v41, v41
	v_exp_f32_e32 v42, v42
	v_exp_f32_e32 v43, v43
	v_exp_f32_e32 v44, v44
	v_exp_f32_e32 v45, v45
	v_exp_f32_e32 v46, v46
	v_exp_f32_e32 v47, v47
	v_exp_f32_e32 v48, v48
	v_exp_f32_e32 v49, v49
	v_pk_fma_f32 v[50:51], v[50:51], v[168:169], v[142:143] op_sel_hi:[1,0,0]
	v_pk_fma_f32 v[52:53], v[52:53], v[168:169], v[142:143] op_sel_hi:[1,0,0]
	v_pk_fma_f32 v[54:55], v[54:55], v[168:169], v[142:143] op_sel_hi:[1,0,0]
	v_pk_fma_f32 v[56:57], v[56:57], v[168:169], v[142:143] op_sel_hi:[1,0,0]
	v_pk_fma_f32 v[58:59], v[58:59], v[168:169], v[142:143] op_sel_hi:[1,0,0]
	v_pk_fma_f32 v[60:61], v[60:61], v[168:169], v[142:143] op_sel_hi:[1,0,0]
	v_pk_fma_f32 v[62:63], v[62:63], v[168:169], v[142:143] op_sel_hi:[1,0,0]
	v_pk_fma_f32 v[64:65], v[64:65], v[168:169], v[142:143] op_sel_hi:[1,0,0]
	v_exp_f32_e32 v50, v50
	v_exp_f32_e32 v51, v51
	v_exp_f32_e32 v52, v52
	v_exp_f32_e32 v53, v53
	v_exp_f32_e32 v54, v54
	v_exp_f32_e32 v55, v55
	v_exp_f32_e32 v56, v56
	v_exp_f32_e32 v57, v57
	v_exp_f32_e32 v58, v58
	v_exp_f32_e32 v59, v59
	v_exp_f32_e32 v60, v60
	v_exp_f32_e32 v61, v61
	v_exp_f32_e32 v62, v62
	v_exp_f32_e32 v63, v63
	v_exp_f32_e32 v64, v64
	v_exp_f32_e32 v65, v65
	ds_read_b64_tr_b16 v[188:189], v179 offset:18432
	ds_read_b64_tr_b16 v[190:191], v179 offset:19584
	ds_read_b64_tr_b16 v[192:193], v179 offset:18496
	ds_read_b64_tr_b16 v[194:195], v179 offset:19648
	ds_read_b64_tr_b16 v[196:197], v179 offset:20736
	ds_read_b64_tr_b16 v[198:199], v179 offset:21888
	ds_read_b64_tr_b16 v[200:201], v179 offset:20800
	ds_read_b64_tr_b16 v[202:203], v179 offset:21952
	ds_read_b64_tr_b16 v[204:205], v179 offset:23040
	ds_read_b64_tr_b16 v[206:207], v179 offset:24192
	v_pk_add_f32 v[220:221], v[34:35], v[220:221]
	v_pk_add_f32 v[220:221], v[36:37], v[220:221]
	v_pk_add_f32 v[220:221], v[38:39], v[220:221]
	v_pk_add_f32 v[220:221], v[40:41], v[220:221]
	v_pk_add_f32 v[220:221], v[42:43], v[220:221]
	v_pk_add_f32 v[220:221], v[44:45], v[220:221]
	v_pk_add_f32 v[220:221], v[46:47], v[220:221]
	v_pk_add_f32 v[220:221], v[48:49], v[220:221]
	v_cvt_pk_bf16_f32 v34, v34, v35
	v_cvt_pk_bf16_f32 v35, v36, v37
	v_cvt_pk_bf16_f32 v36, v38, v39
	v_cvt_pk_bf16_f32 v37, v40, v41
	v_cvt_pk_bf16_f32 v42, v42, v43
	v_cvt_pk_bf16_f32 v43, v44, v45
	v_cvt_pk_bf16_f32 v44, v46, v47
	v_cvt_pk_bf16_f32 v45, v48, v49
	v_pk_add_f32 v[220:221], v[50:51], v[220:221]
	v_pk_add_f32 v[220:221], v[52:53], v[220:221]
	v_pk_add_f32 v[220:221], v[54:55], v[220:221]
	v_pk_add_f32 v[220:221], v[56:57], v[220:221]
	v_pk_add_f32 v[220:221], v[58:59], v[220:221]
	v_pk_add_f32 v[220:221], v[60:61], v[220:221]
	v_pk_add_f32 v[220:221], v[62:63], v[220:221]
	v_pk_add_f32 v[220:221], v[64:65], v[220:221]
	v_cvt_pk_bf16_f32 v50, v50, v51
	v_cvt_pk_bf16_f32 v51, v52, v53
	v_cvt_pk_bf16_f32 v52, v54, v55
	v_cvt_pk_bf16_f32 v53, v56, v57
	v_cvt_pk_bf16_f32 v58, v58, v59
	v_cvt_pk_bf16_f32 v59, v60, v61
	v_cvt_pk_bf16_f32 v60, v62, v63
	v_cvt_pk_bf16_f32 v61, v64, v65
	v_pk_fma_f32 v[66:67], v[66:67], v[168:169], v[144:145] op_sel_hi:[1,0,0]
	v_pk_fma_f32 v[68:69], v[68:69], v[168:169], v[144:145] op_sel_hi:[1,0,0]
	v_pk_fma_f32 v[70:71], v[70:71], v[168:169], v[144:145] op_sel_hi:[1,0,0]
	v_pk_fma_f32 v[72:73], v[72:73], v[168:169], v[144:145] op_sel_hi:[1,0,0]
	v_pk_fma_f32 v[74:75], v[74:75], v[168:169], v[144:145] op_sel_hi:[1,0,0]
	v_pk_fma_f32 v[76:77], v[76:77], v[168:169], v[144:145] op_sel_hi:[1,0,0]
	v_pk_fma_f32 v[78:79], v[78:79], v[168:169], v[144:145] op_sel_hi:[1,0,0]
	v_pk_fma_f32 v[80:81], v[80:81], v[168:169], v[144:145] op_sel_hi:[1,0,0]
	v_exp_f32_e32 v66, v66
	v_exp_f32_e32 v67, v67
	v_exp_f32_e32 v68, v68
	v_exp_f32_e32 v69, v69
	v_exp_f32_e32 v70, v70
	v_exp_f32_e32 v71, v71
	v_exp_f32_e32 v72, v72
	v_exp_f32_e32 v73, v73
	v_exp_f32_e32 v74, v74
	v_exp_f32_e32 v75, v75
	v_exp_f32_e32 v76, v76
	v_exp_f32_e32 v77, v77
	v_exp_f32_e32 v78, v78
	v_exp_f32_e32 v79, v79
	v_exp_f32_e32 v80, v80
	v_exp_f32_e32 v81, v81
	v_pk_fma_f32 v[82:83], v[82:83], v[168:169], v[144:145] op_sel_hi:[1,0,0]
	v_pk_fma_f32 v[84:85], v[84:85], v[168:169], v[144:145] op_sel_hi:[1,0,0]
	v_pk_fma_f32 v[86:87], v[86:87], v[168:169], v[144:145] op_sel_hi:[1,0,0]
	v_pk_fma_f32 v[88:89], v[88:89], v[168:169], v[144:145] op_sel_hi:[1,0,0]
	v_pk_fma_f32 v[90:91], v[90:91], v[168:169], v[144:145] op_sel_hi:[1,0,0]
	v_pk_fma_f32 v[92:93], v[92:93], v[168:169], v[144:145] op_sel_hi:[1,0,0]
	v_pk_fma_f32 v[94:95], v[94:95], v[168:169], v[144:145] op_sel_hi:[1,0,0]
	v_pk_fma_f32 v[96:97], v[96:97], v[168:169], v[144:145] op_sel_hi:[1,0,0]
	v_exp_f32_e32 v82, v82
	v_exp_f32_e32 v83, v83
	v_exp_f32_e32 v84, v84
	v_exp_f32_e32 v85, v85
	v_exp_f32_e32 v86, v86
	v_exp_f32_e32 v87, v87
	v_exp_f32_e32 v88, v88
	v_exp_f32_e32 v89, v89
	v_exp_f32_e32 v90, v90
	v_exp_f32_e32 v91, v91
	v_exp_f32_e32 v92, v92
	v_exp_f32_e32 v93, v93
	v_exp_f32_e32 v94, v94
	v_exp_f32_e32 v95, v95
	v_exp_f32_e32 v96, v96
	v_exp_f32_e32 v97, v97
	v_pk_add_f32 v[220:221], v[66:67], v[220:221]
	v_pk_add_f32 v[220:221], v[68:69], v[220:221]
	v_pk_add_f32 v[220:221], v[70:71], v[220:221]
	v_pk_add_f32 v[220:221], v[72:73], v[220:221]
	v_pk_add_f32 v[220:221], v[74:75], v[220:221]
	v_pk_add_f32 v[220:221], v[76:77], v[220:221]
	v_pk_add_f32 v[220:221], v[78:79], v[220:221]
	v_pk_add_f32 v[220:221], v[80:81], v[220:221]
	v_cvt_pk_bf16_f32 v66, v66, v67
	v_cvt_pk_bf16_f32 v67, v68, v69
	v_cvt_pk_bf16_f32 v68, v70, v71
	v_cvt_pk_bf16_f32 v69, v72, v73
	v_cvt_pk_bf16_f32 v74, v74, v75
	v_cvt_pk_bf16_f32 v75, v76, v77
	v_cvt_pk_bf16_f32 v76, v78, v79
	v_cvt_pk_bf16_f32 v77, v80, v81
	v_pk_add_f32 v[220:221], v[82:83], v[220:221]
	v_pk_add_f32 v[220:221], v[84:85], v[220:221]
	v_pk_add_f32 v[220:221], v[86:87], v[220:221]
	v_pk_add_f32 v[220:221], v[88:89], v[220:221]
	v_pk_add_f32 v[220:221], v[90:91], v[220:221]
	v_pk_add_f32 v[220:221], v[92:93], v[220:221]
	v_pk_add_f32 v[220:221], v[94:95], v[220:221]
	v_pk_add_f32 v[220:221], v[96:97], v[220:221]
	v_cvt_pk_bf16_f32 v82, v82, v83
	v_cvt_pk_bf16_f32 v83, v84, v85
	v_cvt_pk_bf16_f32 v84, v86, v87
	v_cvt_pk_bf16_f32 v85, v88, v89
	v_cvt_pk_bf16_f32 v90, v90, v91
	v_cvt_pk_bf16_f32 v91, v92, v93
	v_cvt_pk_bf16_f32 v92, v94, v95
	v_cvt_pk_bf16_f32 v93, v96, v97
	v_add_f32_e32 v143, v143, v220
	v_add_f32_e32 v143, v143, v221
	s_waitcnt lgkmcnt(8)
	v_mfma_f32_32x32x16_bf16 v[18:33], v[188:191], v[34:37], v[18:33]
	ds_read_b64_tr_b16 v[208:209], v179 offset:23104
	ds_read_b64_tr_b16 v[210:211], v179 offset:24256
	s_waitcnt lgkmcnt(8)
	v_mfma_f32_32x32x16_bf16 v[2:17], v[192:195], v[34:37], v[2:17]
	ds_read_b64_tr_b16 v[212:213], v179 offset:25344
	ds_read_b64_tr_b16 v[214:215], v179 offset:26496
	s_waitcnt lgkmcnt(8)
	v_mfma_f32_32x32x16_bf16 v[18:33], v[196:199], v[42:45], v[18:33]
	ds_read_b64_tr_b16 v[188:189], v179 offset:25408
	ds_read_b64_tr_b16 v[190:191], v179 offset:26560
	s_waitcnt lgkmcnt(8)
	v_mfma_f32_32x32x16_bf16 v[2:17], v[200:203], v[42:45], v[2:17]
	ds_read_b64_tr_b16 v[192:193], v179 offset:27648
	ds_read_b64_tr_b16 v[194:195], v179 offset:28800
	s_waitcnt lgkmcnt(8)
	v_mfma_f32_32x32x16_bf16 v[18:33], v[204:207], v[50:53], v[18:33]
	ds_read_b64_tr_b16 v[196:197], v179 offset:27712
	ds_read_b64_tr_b16 v[198:199], v179 offset:28864
	s_waitcnt lgkmcnt(8)
	v_mfma_f32_32x32x16_bf16 v[2:17], v[208:211], v[50:53], v[2:17]
	ds_read_b64_tr_b16 v[200:201], v179 offset:29952
	ds_read_b64_tr_b16 v[202:203], v179 offset:31104
	s_waitcnt lgkmcnt(8)
	v_mfma_f32_32x32x16_bf16 v[18:33], v[212:215], v[58:61], v[18:33]
	ds_read_b64_tr_b16 v[204:205], v179 offset:30016
	ds_read_b64_tr_b16 v[206:207], v179 offset:31168
	s_waitcnt lgkmcnt(8)
	v_mfma_f32_32x32x16_bf16 v[2:17], v[188:191], v[58:61], v[2:17]
	ds_read_b64_tr_b16 v[208:209], v179 offset:32256
	ds_read_b64_tr_b16 v[210:211], v179 offset:33408
	s_waitcnt lgkmcnt(8)
	v_mfma_f32_32x32x16_bf16 v[18:33], v[192:195], v[66:69], v[18:33]
	ds_read_b64_tr_b16 v[212:213], v179 offset:32320
	ds_read_b64_tr_b16 v[214:215], v179 offset:33472
	s_waitcnt lgkmcnt(8)
	v_mfma_f32_32x32x16_bf16 v[2:17], v[196:199], v[66:69], v[2:17]
	ds_read_b64_tr_b16 v[188:189], v179 offset:34560
	ds_read_b64_tr_b16 v[190:191], v179 offset:35712
	s_waitcnt lgkmcnt(8)
	v_mfma_f32_32x32x16_bf16 v[18:33], v[200:203], v[74:77], v[18:33]
	ds_read_b64_tr_b16 v[192:193], v179 offset:34624
	ds_read_b64_tr_b16 v[194:195], v179 offset:35776
	s_waitcnt lgkmcnt(8)
	v_mfma_f32_32x32x16_bf16 v[2:17], v[204:207], v[74:77], v[2:17]
	s_waitcnt lgkmcnt(6)
	v_mfma_f32_32x32x16_bf16 v[18:33], v[208:211], v[82:85], v[18:33]
	s_waitcnt lgkmcnt(4)
	v_mfma_f32_32x32x16_bf16 v[2:17], v[212:215], v[82:85], v[2:17]
	s_waitcnt lgkmcnt(2)
	v_mfma_f32_32x32x16_bf16 v[18:33], v[188:191], v[90:93], v[18:33]
	s_waitcnt lgkmcnt(0)
	v_mfma_f32_32x32x16_bf16 v[2:17], v[192:195], v[90:93], v[2:17]
	s_branch .LBB0_369
.Lnsa_both_slow:
	v_add3_u32 v1, s90, v151, v152
	ds_read_b128 v[34:37], v1 offset:4608
	ds_read_b128 v[38:41], v1
	ds_read_b128 v[50:53], v1 offset:32
	ds_read_b128 v[54:57], v1 offset:4640
	s_add_i32 s0, s68, 0x7f
	s_waitcnt lgkmcnt(0)
	v_mfma_f32_32x32x16_bf16 v[66:81], v[38:41], v[98:101], 0
	v_mfma_f32_32x32x16_bf16 v[34:49], v[34:37], v[98:101], 0
	v_mfma_f32_32x32x16_bf16 v[66:81], v[50:53], v[102:105], v[66:81]
	v_mfma_f32_32x32x16_bf16 v[34:49], v[54:57], v[102:105], v[34:49]
	ds_read_b128 v[50:53], v1 offset:64
	ds_read_b128 v[54:57], v1 offset:4672
	s_waitcnt lgkmcnt(0)
	v_mfma_f32_32x32x16_bf16 v[66:81], v[50:53], v[106:109], v[66:81]
	v_mfma_f32_32x32x16_bf16 v[34:49], v[54:57], v[106:109], v[34:49]
	ds_read_b128 v[50:53], v1 offset:96
	ds_read_b128 v[54:57], v1 offset:4704
	s_waitcnt lgkmcnt(0)
	v_mfma_f32_32x32x16_bf16 v[66:81], v[50:53], v[110:113], v[66:81]
	v_mfma_f32_32x32x16_bf16 v[34:49], v[54:57], v[110:113], v[34:49]
	ds_read_b128 v[50:53], v1 offset:9216
	ds_read_b128 v[54:57], v1 offset:13824
	ds_read_b128 v[180:183], v1 offset:9248
	ds_read_b128 v[184:187], v1 offset:13856
	s_waitcnt lgkmcnt(0)
	v_mfma_f32_32x32x16_bf16 v[82:97], v[50:53], v[98:101], 0
	v_mfma_f32_32x32x16_bf16 v[50:65], v[54:57], v[98:101], 0
	v_mfma_f32_32x32x16_bf16 v[82:97], v[180:183], v[102:105], v[82:97]
	v_mfma_f32_32x32x16_bf16 v[50:65], v[184:187], v[102:105], v[50:65]
	ds_read_b128 v[180:183], v1 offset:9280
	ds_read_b128 v[184:187], v1 offset:13888
	s_waitcnt lgkmcnt(0)
	v_mfma_f32_32x32x16_bf16 v[82:97], v[180:183], v[106:109], v[82:97]
	v_mfma_f32_32x32x16_bf16 v[50:65], v[184:187], v[106:109], v[50:65]
	ds_read_b128 v[180:183], v1 offset:9312
	ds_read_b128 v[184:187], v1 offset:13920
	v_mov_b32_e32 v1, s87
	v_cndmask_b32_e64 v142, v234, -v1, vcc
	v_cndmask_b32_e64 v179, v234, -v1, s[50:51]
	v_cmp_le_i32_e32 vcc, s0, v176
	v_fmamk_f32 v236, v66, 0x3e38aa3b, v142
	v_fmamk_f32 v235, v67, 0x3e38aa3b, v142
	s_waitcnt lgkmcnt(0)
	v_mfma_f32_32x32x16_bf16 v[82:97], v[180:183], v[110:113], v[82:97]
	v_fmamk_f32 v222, v68, 0x3e38aa3b, v142
	v_fmamk_f32 v1, v69, 0x3e38aa3b, v142
	v_fmamk_f32 v252, v70, 0x3e38aa3b, v142
	v_fmamk_f32 v251, v71, 0x3e38aa3b, v142
	v_fmamk_f32 v250, v72, 0x3e38aa3b, v142
	v_fmamk_f32 v249, v73, 0x3e38aa3b, v142
	v_fmamk_f32 v248, v74, 0x3e38aa3b, v142
	v_mfma_f32_32x32x16_bf16 v[50:65], v[184:187], v[110:113], v[50:65]
	v_fmamk_f32 v247, v75, 0x3e38aa3b, v142
	v_fmamk_f32 v246, v76, 0x3e38aa3b, v142
	v_fmamk_f32 v245, v77, 0x3e38aa3b, v142
	v_fmamk_f32 v243, v78, 0x3e38aa3b, v142
	v_fmamk_f32 v244, v79, 0x3e38aa3b, v142
	v_fmamk_f32 v242, v80, 0x3e38aa3b, v142
	v_fmamk_f32 v241, v81, 0x3e38aa3b, v142
	v_fmamk_f32 v240, v34, 0x3e38aa3b, v142
	v_fmamk_f32 v239, v35, 0x3e38aa3b, v142
	v_fmamk_f32 v238, v36, 0x3e38aa3b, v142
	v_fmamk_f32 v237, v37, 0x3e38aa3b, v142
	v_fmamk_f32 v221, v38, 0x3e38aa3b, v142
	v_fmamk_f32 v220, v39, 0x3e38aa3b, v142
	v_fmamk_f32 v219, v40, 0x3e38aa3b, v142
	v_fmamk_f32 v218, v41, 0x3e38aa3b, v142
	v_fmamk_f32 v217, v42, 0x3e38aa3b, v142
	v_fmamk_f32 v216, v43, 0x3e38aa3b, v142
	v_fmamk_f32 v214, v44, 0x3e38aa3b, v142
	v_fmamk_f32 v215, v45, 0x3e38aa3b, v142
	v_fmamk_f32 v213, v46, 0x3e38aa3b, v142
	v_fmamk_f32 v212, v47, 0x3e38aa3b, v142
	v_fmamk_f32 v211, v48, 0x3e38aa3b, v142
	v_fmac_f32_e32 v142, 0x3e38aa3b, v49
	v_fmamk_f32 v210, v82, 0x3e38aa3b, v179
	v_fmamk_f32 v209, v83, 0x3e38aa3b, v179
	v_fmamk_f32 v208, v84, 0x3e38aa3b, v179
	v_fmamk_f32 v207, v85, 0x3e38aa3b, v179
	v_fmamk_f32 v206, v86, 0x3e38aa3b, v179
	v_fmamk_f32 v205, v87, 0x3e38aa3b, v179
	v_fmamk_f32 v204, v88, 0x3e38aa3b, v179
	v_fmamk_f32 v203, v89, 0x3e38aa3b, v179
	v_fmamk_f32 v201, v90, 0x3e38aa3b, v179
	v_fmamk_f32 v202, v91, 0x3e38aa3b, v179
	v_fmamk_f32 v200, v92, 0x3e38aa3b, v179
	v_fmamk_f32 v199, v93, 0x3e38aa3b, v179
	v_fmamk_f32 v198, v94, 0x3e38aa3b, v179
	v_fmamk_f32 v197, v95, 0x3e38aa3b, v179
	v_fmamk_f32 v196, v96, 0x3e38aa3b, v179
	v_fmamk_f32 v195, v97, 0x3e38aa3b, v179
	v_fmamk_f32 v194, v50, 0x3e38aa3b, v179
	v_fmamk_f32 v193, v51, 0x3e38aa3b, v179
	v_fmamk_f32 v192, v52, 0x3e38aa3b, v179
	v_fmamk_f32 v191, v53, 0x3e38aa3b, v179
	v_fmamk_f32 v190, v54, 0x3e38aa3b, v179
	v_fmamk_f32 v189, v55, 0x3e38aa3b, v179
	v_fmamk_f32 v188, v56, 0x3e38aa3b, v179
	v_fmamk_f32 v187, v57, 0x3e38aa3b, v179
	v_fmamk_f32 v186, v58, 0x3e38aa3b, v179
	v_fmamk_f32 v185, v59, 0x3e38aa3b, v179
	v_fmamk_f32 v184, v60, 0x3e38aa3b, v179
	v_fmamk_f32 v183, v61, 0x3e38aa3b, v179
	v_fmamk_f32 v182, v62, 0x3e38aa3b, v179
	v_fmamk_f32 v181, v63, 0x3e38aa3b, v179
	v_fmamk_f32 v180, v64, 0x3e38aa3b, v179
	v_fmac_f32_e32 v179, 0x3e38aa3b, v65
	s_and_saveexec_b64 s[0:1], vcc
	s_xor_b64 s[0:1], exec, s[0:1]
	s_cbranch_execz .LBB0_366
	v_exp_f32_e32 v34, v236
	v_exp_f32_e32 v35, v235
	v_exp_f32_e32 v44, v240
	v_exp_f32_e32 v36, v222
	v_exp_f32_e32 v45, v239
	v_exp_f32_e32 v37, v1
	v_exp_f32_e32 v46, v238
	v_exp_f32_e32 v38, v252
	v_exp_f32_e32 v47, v237
	v_add_f32_e32 v1, 0, v34
	v_mov_b32_e32 v54, v44
	v_mov_b32_e32 v55, v35
	v_pk_add_f32 v[54:55], v[54:55], v[0:1]
	v_mov_b32_e32 v56, v45
	v_mov_b32_e32 v57, v36
	v_pk_add_f32 v[54:55], v[56:57], v[54:55]
	v_mov_b32_e32 v56, v46
	v_mov_b32_e32 v57, v37
	v_pk_add_f32 v[54:55], v[56:57], v[54:55]
	v_mov_b32_e32 v56, v47
	v_mov_b32_e32 v57, v38
	v_exp_f32_e32 v39, v251
	v_pk_add_f32 v[66:67], v[56:57], v[54:55]
	v_exp_f32_e32 v54, v221
	v_exp_f32_e32 v42, v250
	v_exp_f32_e32 v55, v220
	v_exp_f32_e32 v43, v249
	v_exp_f32_e32 v56, v219
	v_exp_f32_e32 v40, v248
	v_exp_f32_e32 v57, v218
	v_exp_f32_e32 v41, v247
	v_exp_f32_e32 v58, v217
	v_mov_b32_e32 v68, v54
	v_mov_b32_e32 v69, v39
	v_exp_f32_e32 v48, v246
	v_exp_f32_e32 v59, v216
	v_pk_add_f32 v[66:67], v[68:69], v[66:67]
	v_mov_b32_e32 v68, v55
	v_mov_b32_e32 v69, v42
	v_exp_f32_e32 v49, v245
	v_exp_f32_e32 v60, v214
	v_pk_add_f32 v[66:67], v[68:69], v[66:67]
	v_mov_b32_e32 v68, v56
	v_mov_b32_e32 v69, v43
	v_exp_f32_e32 v50, v243
	v_exp_f32_e32 v61, v215
	v_pk_add_f32 v[66:67], v[68:69], v[66:67]
	v_mov_b32_e32 v68, v57
	v_mov_b32_e32 v69, v40
	v_exp_f32_e32 v51, v244
	v_exp_f32_e32 v62, v213
	v_pk_add_f32 v[66:67], v[68:69], v[66:67]
	v_mov_b32_e32 v68, v58
	v_mov_b32_e32 v69, v41
	v_exp_f32_e32 v52, v242
	v_exp_f32_e32 v63, v212
	v_pk_add_f32 v[66:67], v[68:69], v[66:67]
	v_mov_b32_e32 v68, v59
	v_mov_b32_e32 v69, v48
	v_exp_f32_e32 v53, v241
	v_exp_f32_e32 v64, v211
	v_pk_add_f32 v[66:67], v[68:69], v[66:67]
	v_mov_b32_e32 v68, v60
	v_mov_b32_e32 v69, v49
	v_pk_add_f32 v[66:67], v[68:69], v[66:67]
	v_mov_b32_e32 v68, v61
	v_mov_b32_e32 v69, v50
	v_pk_add_f32 v[66:67], v[68:69], v[66:67]
	v_mov_b32_e32 v68, v62
	v_mov_b32_e32 v69, v51
	v_pk_add_f32 v[66:67], v[68:69], v[66:67]
	v_mov_b32_e32 v68, v63
	v_mov_b32_e32 v69, v52
	v_pk_add_f32 v[66:67], v[68:69], v[66:67]
	v_mov_b32_e32 v68, v64
	v_mov_b32_e32 v69, v53
	v_pk_add_f32 v[68:69], v[68:69], v[66:67]
	v_exp_f32_e32 v66, v210
	v_exp_f32_e32 v67, v209
	v_exp_f32_e32 v70, v208
	v_exp_f32_e32 v82, v194
	v_exp_f32_e32 v71, v207
	v_exp_f32_e32 v83, v193
	v_exp_f32_e32 v72, v206
	v_exp_f32_e32 v86, v192
	v_exp_f32_e32 v65, v142
	v_add_f32_e32 v1, 0, v66
	v_exp_f32_e32 v73, v205
	v_exp_f32_e32 v87, v191
	v_add_f32_e32 v1, v67, v1
	v_mov_b32_e32 v88, v82
	v_mov_b32_e32 v89, v70
	v_pk_add_f32 v[88:89], v[88:89], v[0:1]
	v_mov_b32_e32 v90, v83
	v_mov_b32_e32 v91, v71
	v_pk_add_f32 v[88:89], v[90:91], v[88:89]
	v_mov_b32_e32 v90, v86
	v_mov_b32_e32 v91, v72
	v_mov_b32_e32 v142, v65
	v_pk_add_f32 v[88:89], v[90:91], v[88:89]
	v_mov_b32_e32 v90, v87
	v_mov_b32_e32 v91, v73
	v_pk_add_f32 v[68:69], v[142:143], v[68:69]
	v_exp_f32_e32 v74, v204
	v_pk_add_f32 v[142:143], v[90:91], v[88:89]
	v_exp_f32_e32 v88, v190
	v_exp_f32_e32 v75, v203
	v_exp_f32_e32 v89, v189
	v_exp_f32_e32 v76, v201
	v_exp_f32_e32 v90, v188
	v_exp_f32_e32 v77, v202
	v_exp_f32_e32 v91, v187
	v_exp_f32_e32 v78, v200
	v_exp_f32_e32 v92, v186
	v_mov_b32_e32 v144, v88
	v_mov_b32_e32 v145, v74
	v_exp_f32_e32 v79, v199
	v_exp_f32_e32 v93, v185
	v_pk_add_f32 v[142:143], v[144:145], v[142:143]
	v_mov_b32_e32 v144, v89
	v_mov_b32_e32 v145, v75
	v_exp_f32_e32 v80, v198
	v_exp_f32_e32 v94, v184
	v_pk_add_f32 v[142:143], v[144:145], v[142:143]
	v_mov_b32_e32 v144, v90
	v_mov_b32_e32 v145, v76
	v_exp_f32_e32 v81, v197
	v_exp_f32_e32 v95, v183
	v_pk_add_f32 v[142:143], v[144:145], v[142:143]
	v_mov_b32_e32 v144, v91
	v_mov_b32_e32 v145, v77
	v_exp_f32_e32 v84, v196
	v_exp_f32_e32 v96, v182
	v_pk_add_f32 v[142:143], v[144:145], v[142:143]
	v_mov_b32_e32 v144, v92
	v_mov_b32_e32 v145, v78
	v_exp_f32_e32 v85, v195
	v_exp_f32_e32 v97, v181
	v_pk_add_f32 v[142:143], v[144:145], v[142:143]
	v_mov_b32_e32 v144, v93
	v_mov_b32_e32 v145, v79
	v_pk_add_f32 v[68:69], v[68:69], v[68:69] op_sel_hi:[0,1]
	v_pk_add_f32 v[142:143], v[144:145], v[142:143]
	v_mov_b32_e32 v144, v94
	v_mov_b32_e32 v145, v80
	v_pk_add_f32 v[142:143], v[144:145], v[142:143]
	v_mov_b32_e32 v144, v95
	v_mov_b32_e32 v145, v81
	v_exp_f32_e32 v68, v180
	v_pk_add_f32 v[142:143], v[144:145], v[142:143]
	v_mov_b32_e32 v144, v96
	v_mov_b32_e32 v145, v84
	v_pk_add_f32 v[142:143], v[144:145], v[142:143]
	v_mov_b32_e32 v144, v97
	v_mov_b32_e32 v145, v85
	v_pk_add_f32 v[142:143], v[144:145], v[142:143]
	s_nop 0
	v_pk_add_f32 v[144:145], v[68:69], v[142:143]
